# nt hint on the read-once streaming loads of the sample-group phases (hgrn state, K/V caches)
# speedup vs baseline: 1.0036x; 1.0036x over previous
; __device__ __forceinline__ void hgrn_sample(Frame& F) {
;     ...
;         const int b = u >> 2, h = u & 3, row0 = TP + b * 8;
;         float S[32];
; #pragma unroll
;         for (int j = 0; j < 32; ++j) S[j] = F.state_hgrn[(((size_t)b * 4 + h) * 128 + qd * 32 + j) * 128 + dv];
; #pragma unroll
;         for (int i = 0; i < 2; ++i) { const int idx = tid + 512 * i, t = idx >> 7, cc = idx & 127; const size_t ro = (size_t)(row0 + t) * 512 + h * 128 + cc;
;             qs[idx] = bf2f(F.Q[ro]); fs[idx] = __expf((float)F.LOGF[ro]); ks[idx] = 1.f - fs[idx]; }
;         float v[8];
; #pragma unroll
;         for (int t = 0; t < 8; ++t) v[t] = bf2f(F.V[(size_t)(row0 + t) * 512 + h * 128 + dv]);
;         const float ogv = F.onorm_g[h * 128 + dv]; bf16 gsv[2];
; #pragma unroll
;         for (int i = 0; i < 2; ++i) gsv[i] = F.GS[(size_t)(row0 + ((tid + 512 * i) >> 7)) * 512 + h * 128 + dv];
;         __syncthreads();
.LBB0_634:
	s_ashr_i32 s0, s12, 2
	s_lshl_b32 s15, s0, 3
	s_and_b32 s14, s12, 3
	s_add_i32 s6, s15, 0x4000
	s_lshl_b32 s13, s14, 7
	v_or_b32_e32 v18, s6, v3
	v_or_b32_e32 v52, s13, v2
	v_ashrrev_i32_e32 v19, 31, v18
	v_lshlrev_b32_e32 v4, 1, v52
	v_lshlrev_b64 v[36:37], 10, v[18:19]
	v_or_b32_e32 v16, v36, v4
	v_mov_b32_e32 v17, v37
	v_lshl_add_u64 v[34:35], s[66:67], 0, v[16:17]
	v_lshl_add_u64 v[38:39], s[72:73], 0, v[16:17]
	v_or_b32_e32 v16, s6, v29
	v_ashrrev_i32_e32 v17, 31, v16
	v_lshlrev_b64 v[44:45], 10, v[16:17]
	v_or_b32_e32 v40, v44, v4
	v_mov_b32_e32 v41, v45
	s_lshl_b32 s4, s14, 8
	s_ashr_i32 s7, s6, 31
	v_lshl_add_u64 v[42:43], s[66:67], 0, v[40:41]
	v_lshl_add_u64 v[40:41], s[72:73], 0, v[40:41]
	global_load_ushort v53, v[38:39], off
	s_waitcnt lgkmcnt(0)
	global_load_ushort v54, v[40:41], off
	v_lshl_add_u64 v[38:39], v[10:11], 0, s[4:5]
	s_lshl_b64 s[6:7], s[6:7], 10
	v_lshl_add_u64 v[40:41], v[38:39], 0, s[6:7]
	s_add_i32 s6, s15, 0x4001
	s_ashr_i32 s7, s6, 31
	s_lshl_b64 s[6:7], s[6:7], 10
	v_lshl_add_u64 v[46:47], v[38:39], 0, s[6:7]
	s_add_i32 s6, s15, 0x4002
	s_ashr_i32 s7, s6, 31
	s_lshl_b64 s[6:7], s[6:7], 10
	v_lshl_add_u64 v[48:49], v[38:39], 0, s[6:7]
	s_add_i32 s6, s15, 0x4003
	s_ashr_i32 s7, s6, 31
	s_lshl_b64 s[6:7], s[6:7], 10
	v_lshl_add_u64 v[50:51], v[38:39], 0, s[6:7]
	s_add_i32 s6, s15, 0x4004
	s_ashr_i32 s7, s6, 31
	s_lshl_b64 s[6:7], s[6:7], 10
	global_load_ushort v55, v[34:35], off
	s_nop 0
	global_load_ushort v42, v[42:43], off
	s_nop 0
	global_load_ushort v43, v[40:41], off
	s_nop 0
	global_load_ushort v46, v[46:47], off
	s_nop 0
	global_load_ushort v47, v[48:49], off
	s_nop 0
	global_load_ushort v48, v[50:51], off
	v_lshl_add_u64 v[34:35], v[38:39], 0, s[6:7]
	s_add_i32 s6, s15, 0x4005
	s_ashr_i32 s7, s6, 31
	s_lshl_b64 s[6:7], s[6:7], 10
	v_lshl_add_u64 v[40:41], v[38:39], 0, s[6:7]
	s_add_i32 s6, s15, 0x4006
	s_ashr_i32 s7, s6, 31
	s_lshl_b64 s[6:7], s[6:7], 10
	global_load_ushort v49, v[34:35], off
	global_load_ushort v50, v[40:41], off
	v_lshl_add_u64 v[34:35], v[38:39], 0, s[6:7]
	s_add_i32 s6, s15, 0x4007
	s_ashr_i32 s7, s6, 31
	s_lshl_b64 s[6:7], s[6:7], 10
	v_lshl_add_u64 v[38:39], v[38:39], 0, s[6:7]
	global_load_ushort v51, v[34:35], off
	global_load_ushort v56, v[38:39], off
	s_ashr_i32 s1, s0, 31
	v_or_b32_e32 v4, s13, v20
	s_lshl_b64 s[6:7], s[0:1], 18
	v_lshlrev_b32_e32 v4, 9, v4
	v_lshl_add_u64 v[34:35], v[8:9], 0, s[6:7]
	v_lshl_add_u64 v[34:35], v[34:35], 0, v[4:5]
	global_load_dword v64, v[34:35], off nt
	global_load_dword v76, v[34:35], off offset:512 nt
	global_load_dword v77, v[34:35], off offset:1024 nt
	global_load_dword v78, v[34:35], off offset:1536 nt
	global_load_dword v79, v[34:35], off offset:2048 nt
	global_load_dword v80, v[34:35], off offset:2560 nt
	global_load_dword v81, v[34:35], off offset:3072 nt
	global_load_dword v82, v[34:35], off offset:3584 nt
	v_add_co_u32_e64 v38, s[0:1], s9, v34
	v_readlane_b32 s16, v254, 23
	s_nop 0
	v_addc_co_u32_e64 v39, s[0:1], 0, v35, s[0:1]
	v_add_co_u32_e64 v40, s[0:1], s10, v34
	v_readlane_b32 s26, v254, 33
	s_nop 0
	v_addc_co_u32_e64 v41, s[0:1], 0, v35, s[0:1]
	v_add_co_u32_e64 v34, s[0:1], s11, v34
	global_load_dword v83, v[40:41], off offset:-4096 nt
	global_load_dword v84, v[40:41], off nt
	global_load_dword v85, v[40:41], off offset:512 nt
	global_load_dword v86, v[40:41], off offset:1024 nt
	global_load_dword v87, v[40:41], off offset:1536 nt
	global_load_dword v88, v[40:41], off offset:2048 nt
	global_load_dword v89, v[40:41], off offset:2560 nt
	global_load_dword v90, v[40:41], off offset:3072 nt
	global_load_dword v91, v[40:41], off offset:3584 nt
	v_addc_co_u32_e64 v35, s[0:1], 0, v35, s[0:1]
	global_load_dword v92, v[38:39], off offset:512 nt
	global_load_dword v93, v[38:39], off offset:1024 nt
	global_load_dword v94, v[38:39], off offset:1536 nt
	global_load_dword v95, v[38:39], off offset:2048 nt
	global_load_dword v96, v[38:39], off offset:2560 nt
	global_load_dword v97, v[38:39], off offset:3072 nt
	global_load_dword v98, v[38:39], off offset:3584 nt
	global_load_dword v99, v[34:35], off nt
	global_load_dword v100, v[34:35], off offset:512 nt
	global_load_dword v101, v[34:35], off offset:1024 nt
	global_load_dword v102, v[34:35], off offset:1536 nt
	global_load_dword v103, v[34:35], off offset:2048 nt
	global_load_dword v104, v[34:35], off offset:2560 nt
	global_load_dword v105, v[34:35], off offset:3072 nt
	global_load_dword v106, v[34:35], off offset:3584 nt
	v_readlane_b32 s27, v254, 34
	s_add_u32 s0, s33, s6
	s_addc_u32 s1, s42, s7
	v_readlane_b32 s17, v254, 24
	v_readlane_b32 s18, v254, 25
	v_readlane_b32 s19, v254, 26
	v_readlane_b32 s20, v254, 27
	v_readlane_b32 s21, v254, 28
	v_readlane_b32 s22, v254, 29
	v_readlane_b32 s23, v254, 30
	v_readlane_b32 s24, v254, 31
	v_readlane_b32 s25, v254, 32
	v_readlane_b32 s28, v254, 35
	v_readlane_b32 s29, v254, 36
	v_readlane_b32 s30, v254, 37
	v_readlane_b32 s31, v254, 38
	s_waitcnt vmcnt(0)
	v_cvt_f32_f16_e32 v4, v53
	v_cvt_f32_f16_e32 v34, v54
	v_mul_f32_e32 v4, 0x3fb8aa3b, v4
	v_mul_f32_e32 v34, 0x3fb8aa3b, v34
	v_exp_f32_e32 v4, v4
	v_exp_f32_e32 v34, v34
	v_sub_f32_e32 v38, 1.0, v4
	v_lshlrev_b32_e32 v35, 16, v55
	v_lshlrev_b32_e32 v39, 16, v42
	ds_write2st64_b32 v28, v35, v39 offset1:8
	ds_write2st64_b32 v28, v4, v34 offset0:16 offset1:24
	v_sub_f32_e32 v4, 1.0, v34
	v_lshlrev_b32_e32 v42, 16, v46
	v_lshlrev_b32_e32 v41, 16, v47
	v_lshl_add_u64 v[46:47], v[12:13], 0, s[4:5]
	ds_write2st64_b32 v28, v38, v4 offset0:32 offset1:40
	v_lshlrev_b32_e32 v4, 2, v52
	v_lshl_add_u64 v[36:37], v[46:47], 0, v[36:37]
	v_lshl_add_u64 v[44:45], v[46:47], 0, v[44:45]
	global_load_dword v34, v4, s[26:27] nt
	s_nop 0
	global_load_ushort v4, v[36:37], off
	global_load_ushort v35, v[44:45], off
	s_waitcnt lgkmcnt(0)
	s_barrier
; #define LAS __attribute__((address_space(3)))
; __device__ __forceinline__ void hgrn_sample(Frame& F) {
;     ...
; #pragma unroll
;         for (int t = 0; t < 8; ++t) { float op = 0.f;
; #pragma unroll
;             for (int j4 = 0; j4 < 8; ++j4) { const f32x4 f4 = *(const LAS f32x4*)(fs + t * 128 + qd * 32 + 4 * j4), k4 = *(const LAS f32x4*)(ks + t * 128 + qd * 32 + 4 * j4), q4 = *(const LAS f32x4*)(qs + t * 128 + qd * 32 + 4 * j4);
; #pragma unroll
;                 for (int e = 0; e < 4; ++e) { float s = f4[e] * S[4 * j4 + e] + k4[e] * v[t]; S[4 * j4 + e] = s; op += q4[e] * s; } }
;             part[(qd * 8 + t) * 128 + dv] = op; }
	ds_read_b128 v[44:47], v21 offset:8192
	v_lshlrev_b32_e32 v40, 16, v48
	v_lshlrev_b32_e32 v39, 16, v49
	v_lshlrev_b32_e32 v38, 16, v50
	v_lshlrev_b32_e32 v37, 16, v51
	ds_read_b128 v[48:51], v21 offset:4096
	ds_read_b128 v[52:55], v21 offset:8208
	v_lshlrev_b32_e32 v43, 16, v43
	v_lshlrev_b32_e32 v36, 16, v56
	ds_read_b128 v[56:59], v21
	ds_read_b128 v[60:63], v21 offset:4112
	s_waitcnt lgkmcnt(4)
	v_mul_f32_e32 v109, v45, v43
	v_mul_f32_e32 v107, v44, v43
	s_waitcnt lgkmcnt(3)
	v_fmac_f32_e32 v109, v76, v49
	v_mul_f32_e32 v76, v46, v43
	v_fmac_f32_e32 v107, v64, v48
	ds_read_b128 v[64:67], v21 offset:16
	ds_read_b128 v[68:71], v21 offset:32
	ds_read_b128 v[72:75], v21 offset:48
	v_fmac_f32_e32 v76, v77, v50
	v_mul_f32_e32 v77, v47, v43
	ds_read_b128 v[44:47], v21 offset:8224
	v_fmac_f32_e32 v77, v78, v51
	s_waitcnt lgkmcnt(6)
	v_mul_f32_e32 v78, v52, v43
	ds_read_b128 v[48:51], v21 offset:4128
	s_waitcnt lgkmcnt(6)
	v_fma_f32 v108, v56, v107, 0
	s_waitcnt lgkmcnt(5)
	v_fmac_f32_e32 v78, v79, v60
	v_mul_f32_e32 v79, v53, v43
	v_fmac_f32_e32 v108, v57, v109
	v_fmac_f32_e32 v79, v80, v61
	v_mul_f32_e32 v80, v54, v43
	v_fmac_f32_e32 v108, v58, v76
	v_fmac_f32_e32 v80, v81, v62
	v_mul_f32_e32 v81, v55, v43
	ds_read_b128 v[52:55], v21 offset:8240
	v_fmac_f32_e32 v108, v59, v77
	v_fmac_f32_e32 v81, v82, v63
	s_waitcnt lgkmcnt(2)
	v_mul_f32_e32 v82, v44, v43
	ds_read_b128 v[56:59], v21 offset:4144
	s_waitcnt lgkmcnt(2)
	v_fmac_f32_e32 v82, v83, v48
	v_mul_f32_e32 v83, v45, v43
	v_fmac_f32_e32 v108, v64, v78
	v_fmac_f32_e32 v83, v92, v49
	v_mul_f32_e32 v92, v46, v43
	v_fmac_f32_e32 v108, v65, v79
	v_fmac_f32_e32 v92, v93, v50
	v_mul_f32_e32 v93, v47, v43
	v_fmac_f32_e32 v108, v66, v80
	v_fmac_f32_e32 v93, v94, v51
	s_waitcnt lgkmcnt(1)
	v_mul_f32_e32 v94, v52, v43
	v_fmac_f32_e32 v108, v67, v81
	s_waitcnt lgkmcnt(0)
	v_fmac_f32_e32 v94, v95, v56
	v_mul_f32_e32 v95, v53, v43
	ds_read_b128 v[44:47], v21 offset:8256
	v_fmac_f32_e32 v108, v68, v82
	v_fmac_f32_e32 v95, v96, v57
	v_mul_f32_e32 v96, v54, v43
	v_fmac_f32_e32 v108, v69, v83
	v_fmac_f32_e32 v96, v97, v58
	v_mul_f32_e32 v97, v55, v43
	v_fmac_f32_e32 v108, v70, v92
	v_fmac_f32_e32 v97, v98, v59
	ds_read_b128 v[48:51], v21 offset:4160
	ds_read_b128 v[52:55], v21 offset:64
	ds_read_b128 v[56:59], v21 offset:8272
	v_fmac_f32_e32 v108, v71, v93
	v_fmac_f32_e32 v108, v72, v94
	s_waitcnt lgkmcnt(3)
	v_mul_f32_e32 v98, v44, v43
	ds_read_b128 v[60:63], v21 offset:4176
	ds_read_b128 v[64:67], v21 offset:80
	v_fmac_f32_e32 v108, v73, v95
	s_waitcnt lgkmcnt(4)
	v_fmac_f32_e32 v98, v84, v48
	v_mul_f32_e32 v84, v45, v43
	v_fmac_f32_e32 v108, v74, v96
	v_fmac_f32_e32 v84, v85, v49
	v_mul_f32_e32 v85, v46, v43
	v_fmac_f32_e32 v108, v75, v97
	v_fmac_f32_e32 v85, v86, v50
	v_mul_f32_e32 v86, v47, v43
	s_waitcnt lgkmcnt(3)
	v_fmac_f32_e32 v108, v52, v98
	v_fmac_f32_e32 v86, v87, v51
	s_waitcnt lgkmcnt(2)
	v_mul_f32_e32 v87, v56, v43
	ds_read_b128 v[44:47], v21 offset:8288
	v_fmac_f32_e32 v108, v53, v84
	s_waitcnt lgkmcnt(2)
	v_fmac_f32_e32 v87, v88, v60
	v_mul_f32_e32 v88, v57, v43
	v_fmac_f32_e32 v108, v54, v85
	v_fmac_f32_e32 v88, v89, v61
	v_mul_f32_e32 v89, v58, v43
	v_fmac_f32_e32 v108, v55, v86
	v_fmac_f32_e32 v89, v90, v62
	v_mul_f32_e32 v90, v59, v43
	ds_read_b128 v[48:51], v21 offset:4192
	ds_read_b128 v[52:55], v21 offset:96
	ds_read_b128 v[56:59], v21 offset:8304
	s_waitcnt lgkmcnt(4)
	v_fmac_f32_e32 v108, v64, v87
	v_fmac_f32_e32 v108, v65, v88
	v_fmac_f32_e32 v90, v91, v63
	s_waitcnt lgkmcnt(3)
	v_mul_f32_e32 v91, v44, v43
	ds_read_b128 v[60:63], v21 offset:4208
	v_fmac_f32_e32 v108, v66, v89
	s_waitcnt lgkmcnt(3)
	v_fmac_f32_e32 v91, v99, v48
	v_mul_f32_e32 v99, v45, v43
	v_fmac_f32_e32 v108, v67, v90
	v_fmac_f32_e32 v99, v100, v49
	v_mul_f32_e32 v100, v46, v43
	s_waitcnt lgkmcnt(2)
	v_fmac_f32_e32 v108, v52, v91
	v_fmac_f32_e32 v100, v101, v50
	v_mul_f32_e32 v101, v47, v43
	ds_read_b128 v[64:67], v21 offset:112
	v_fmac_f32_e32 v108, v53, v99
	v_fmac_f32_e32 v101, v102, v51
	s_waitcnt lgkmcnt(2)
	v_mul_f32_e32 v102, v56, v43
	ds_read_b128 v[44:47], v21 offset:8704
	v_fmac_f32_e32 v108, v54, v100
	s_waitcnt lgkmcnt(2)
	v_fmac_f32_e32 v102, v103, v60
	v_mul_f32_e32 v103, v57, v43
	v_fmac_f32_e32 v108, v55, v101
	v_fmac_f32_e32 v103, v104, v61
	v_mul_f32_e32 v104, v58, v43
	v_mul_f32_e32 v43, v59, v43
	ds_read_b128 v[48:51], v21 offset:4608
	ds_read_b128 v[52:55], v21 offset:8720
	v_fmac_f32_e32 v104, v105, v62
	v_fmac_f32_e32 v43, v106, v63
	ds_read_b128 v[56:59], v21 offset:512
	ds_read_b128 v[60:63], v21 offset:4624
	s_waitcnt lgkmcnt(5)
	v_fmac_f32_e32 v108, v64, v102
	s_waitcnt lgkmcnt(4)
	v_mul_f32_e32 v105, v44, v42
	v_fmac_f32_e32 v108, v65, v103
	s_waitcnt lgkmcnt(3)
	v_fmac_f32_e32 v105, v107, v48
	v_mul_f32_e32 v107, v45, v42
	v_fmac_f32_e32 v108, v66, v104
	s_waitcnt lgkmcnt(1)
	v_fma_f32 v106, v56, v105, 0
	v_fmac_f32_e32 v107, v109, v49
	v_mul_f32_e32 v109, v46, v42
	v_fmac_f32_e32 v108, v67, v43
	ds_read_b128 v[64:67], v21 offset:528
	ds_read_b128 v[68:71], v21 offset:544
	ds_read_b128 v[72:75], v21 offset:560
	v_fmac_f32_e32 v106, v57, v107
	v_fmac_f32_e32 v109, v76, v50
	v_mul_f32_e32 v76, v47, v42
	ds_read_b128 v[44:47], v21 offset:8736
	v_fmac_f32_e32 v106, v58, v109
	v_fmac_f32_e32 v76, v77, v51
	v_mul_f32_e32 v77, v52, v42
	ds_read_b128 v[48:51], v21 offset:4640
	v_fmac_f32_e32 v106, v59, v76
	s_waitcnt lgkmcnt(5)
	v_fmac_f32_e32 v77, v78, v60
	v_mul_f32_e32 v78, v53, v42
	s_waitcnt lgkmcnt(4)
	v_fmac_f32_e32 v106, v64, v77
	v_fmac_f32_e32 v78, v79, v61
	v_mul_f32_e32 v79, v54, v42
	v_fmac_f32_e32 v106, v65, v78
	v_fmac_f32_e32 v79, v80, v62
	v_mul_f32_e32 v80, v55, v42
	ds_read_b128 v[52:55], v21 offset:8752
	v_fmac_f32_e32 v106, v66, v79
	v_fmac_f32_e32 v80, v81, v63
	s_waitcnt lgkmcnt(2)
; #define LAS __attribute__((address_space(3)))
; __device__ __forceinline__ void hgrn_sample(Frame& F) {
;     ...
; #pragma unroll
;         for (int t = 0; t < 8; ++t) { float op = 0.f;
; #pragma unroll
;             for (int j4 = 0; j4 < 8; ++j4) { const f32x4 f4 = *(const LAS f32x4*)(fs + t * 128 + qd * 32 + 4 * j4), k4 = *(const LAS f32x4*)(ks + t * 128 + qd * 32 + 4 * j4), q4 = *(const LAS f32x4*)(qs + t * 128 + qd * 32 + 4 * j4);
; #pragma unroll
;                 for (int e = 0; e < 4; ++e) { float s = f4[e] * S[4 * j4 + e] + k4[e] * v[t]; S[4 * j4 + e] = s; op += q4[e] * s; } }
;             part[(qd * 8 + t) * 128 + dv] = op; }
	v_mul_f32_e32 v81, v44, v42
	ds_read_b128 v[56:59], v21 offset:4656
	v_fmac_f32_e32 v106, v67, v80
	s_waitcnt lgkmcnt(2)
	v_fmac_f32_e32 v81, v82, v48
	v_mul_f32_e32 v82, v45, v42
	v_fmac_f32_e32 v106, v68, v81
	v_fmac_f32_e32 v82, v83, v49
	v_mul_f32_e32 v83, v46, v42
	v_fmac_f32_e32 v106, v69, v82
	v_fmac_f32_e32 v83, v92, v50
	v_mul_f32_e32 v92, v47, v42
	v_fmac_f32_e32 v106, v70, v83
	v_fmac_f32_e32 v92, v93, v51
	s_waitcnt lgkmcnt(1)
	v_mul_f32_e32 v93, v52, v42
	v_fmac_f32_e32 v106, v71, v92
	s_waitcnt lgkmcnt(0)
	v_fmac_f32_e32 v93, v94, v56
	v_mul_f32_e32 v94, v53, v42
	v_fmac_f32_e32 v106, v72, v93
	v_fmac_f32_e32 v94, v95, v57
	v_mul_f32_e32 v95, v54, v42
	ds_read_b128 v[44:47], v21 offset:8768
	v_fmac_f32_e32 v106, v73, v94
	v_fmac_f32_e32 v95, v96, v58
	v_fmac_f32_e32 v106, v74, v95
	v_mul_f32_e32 v74, v55, v42
	v_fmac_f32_e32 v74, v97, v59
	ds_read_b128 v[48:51], v21 offset:4672
	ds_read_b128 v[52:55], v21 offset:576
	ds_read_b128 v[56:59], v21 offset:8784
	ds_read_b128 v[60:63], v21 offset:4688
	ds_read_b128 v[64:67], v21 offset:592
	v_fmac_f32_e32 v106, v75, v74
	s_waitcnt lgkmcnt(5)
	v_mul_f32_e32 v75, v44, v42
	v_mul_f32_e32 v96, v45, v42
	s_waitcnt lgkmcnt(4)
	v_fmac_f32_e32 v75, v98, v48
	v_fmac_f32_e32 v96, v84, v49
	v_mul_f32_e32 v84, v46, v42
	s_waitcnt lgkmcnt(3)
	v_fmac_f32_e32 v106, v52, v75
	v_fmac_f32_e32 v84, v85, v50
	v_mul_f32_e32 v85, v47, v42
	v_fmac_f32_e32 v106, v53, v96
	v_fmac_f32_e32 v85, v86, v51
	s_waitcnt lgkmcnt(2)
	v_mul_f32_e32 v86, v56, v42
	ds_read_b128 v[44:47], v21 offset:8800
	v_fmac_f32_e32 v106, v54, v84
	s_waitcnt lgkmcnt(2)
	v_fmac_f32_e32 v86, v87, v60
	v_mul_f32_e32 v87, v57, v42
	v_fmac_f32_e32 v106, v55, v85
	v_fmac_f32_e32 v87, v88, v61
	v_mul_f32_e32 v88, v58, v42
	s_waitcnt lgkmcnt(1)
	v_fmac_f32_e32 v106, v64, v86
	v_fmac_f32_e32 v88, v89, v62
	v_mul_f32_e32 v89, v59, v42
	ds_read_b128 v[48:51], v21 offset:4704
	ds_read_b128 v[52:55], v21 offset:608
	ds_read_b128 v[56:59], v21 offset:8816
	v_fmac_f32_e32 v106, v65, v87
	v_fmac_f32_e32 v106, v66, v88
	v_fmac_f32_e32 v89, v90, v63
	s_waitcnt lgkmcnt(3)
	v_mul_f32_e32 v90, v44, v42
	ds_read_b128 v[60:63], v21 offset:4720
	v_fmac_f32_e32 v106, v67, v89
	s_waitcnt lgkmcnt(3)
	v_fmac_f32_e32 v90, v91, v48
	ds_read_b128 v[64:67], v21 offset:624
	v_mul_f32_e32 v91, v45, v42
	s_waitcnt lgkmcnt(3)
	v_fmac_f32_e32 v106, v52, v90
	v_fmac_f32_e32 v91, v99, v49
	v_mul_f32_e32 v97, v46, v42
	v_fmac_f32_e32 v106, v53, v91
	v_fmac_f32_e32 v97, v100, v50
	v_mul_f32_e32 v98, v47, v42
	v_fmac_f32_e32 v106, v54, v97
	v_fmac_f32_e32 v98, v101, v51
	s_waitcnt lgkmcnt(2)
	v_mul_f32_e32 v99, v56, v42
	v_fmac_f32_e32 v106, v55, v98
	s_waitcnt lgkmcnt(1)
	v_fmac_f32_e32 v99, v102, v60
	v_mul_f32_e32 v100, v57, v42
	s_waitcnt lgkmcnt(0)
	v_fmac_f32_e32 v106, v64, v99
	v_fmac_f32_e32 v100, v103, v61
	v_mul_f32_e32 v101, v58, v42
	v_fmac_f32_e32 v106, v65, v100
	v_fmac_f32_e32 v101, v104, v62
	v_mul_f32_e32 v102, v59, v42
	v_fmac_f32_e32 v106, v66, v101
	v_fmac_f32_e32 v102, v43, v63
	ds_read_b128 v[42:45], v21 offset:9216
	v_fmac_f32_e32 v106, v67, v102
	ds_write2st64_b32 v32, v108, v106 offset0:48 offset1:50
	ds_read_b128 v[46:49], v21 offset:5120
	ds_read_b128 v[50:53], v21 offset:9232
	ds_read_b128 v[54:57], v21 offset:1024
	ds_read_b128 v[58:61], v21 offset:5136
	s_waitcnt lgkmcnt(5)
	v_mul_f32_e32 v103, v42, v41
	ds_read_b128 v[62:65], v21 offset:1040
	ds_read_b128 v[66:69], v21 offset:1056
	ds_read_b128 v[70:73], v21 offset:1072
	s_waitcnt lgkmcnt(6)
	v_fmac_f32_e32 v103, v105, v46
	v_mul_f32_e32 v105, v43, v41
	v_fmac_f32_e32 v105, v107, v47
	v_mul_f32_e32 v106, v44, v41
	v_mul_f32_e32 v107, v45, v41
	ds_read_b128 v[42:45], v21 offset:9248
	v_fmac_f32_e32 v106, v109, v48
	v_fmac_f32_e32 v107, v76, v49
	s_waitcnt lgkmcnt(6)
	v_mul_f32_e32 v76, v50, v41
	ds_read_b128 v[46:49], v21 offset:5152
	s_waitcnt lgkmcnt(6)
	v_fma_f32 v104, v54, v103, 0
	s_waitcnt lgkmcnt(5)
	v_fmac_f32_e32 v76, v77, v58
	v_mul_f32_e32 v77, v51, v41
	v_fmac_f32_e32 v104, v55, v105
	v_fmac_f32_e32 v77, v78, v59
	v_mul_f32_e32 v78, v52, v41
	v_fmac_f32_e32 v104, v56, v106
	v_fmac_f32_e32 v78, v79, v60
	v_mul_f32_e32 v79, v53, v41
	ds_read_b128 v[50:53], v21 offset:9264
	v_fmac_f32_e32 v104, v57, v107
	v_fmac_f32_e32 v79, v80, v61
	s_waitcnt lgkmcnt(2)
	v_mul_f32_e32 v80, v42, v41
	ds_read_b128 v[54:57], v21 offset:5168
	s_waitcnt lgkmcnt(2)
	v_fmac_f32_e32 v80, v81, v46
	v_mul_f32_e32 v81, v43, v41
	v_fmac_f32_e32 v104, v62, v76
	v_fmac_f32_e32 v81, v82, v47
	v_mul_f32_e32 v82, v44, v41
	v_fmac_f32_e32 v104, v63, v77
	v_fmac_f32_e32 v82, v83, v48
	v_mul_f32_e32 v83, v45, v41
	v_fmac_f32_e32 v104, v64, v78
	v_fmac_f32_e32 v83, v92, v49
	s_waitcnt lgkmcnt(1)
	v_mul_f32_e32 v92, v50, v41
	v_fmac_f32_e32 v104, v65, v79
	s_waitcnt lgkmcnt(0)
	v_fmac_f32_e32 v92, v93, v54
	v_mul_f32_e32 v93, v51, v41
	ds_read_b128 v[42:45], v21 offset:9280
	v_fmac_f32_e32 v104, v66, v80
	v_fmac_f32_e32 v93, v94, v55
	v_mul_f32_e32 v94, v52, v41
	v_fmac_f32_e32 v104, v67, v81
	v_fmac_f32_e32 v94, v95, v56
	v_mul_f32_e32 v95, v53, v41
	v_fmac_f32_e32 v104, v68, v82
	v_fmac_f32_e32 v95, v74, v57
	ds_read_b128 v[46:49], v21 offset:5184
	ds_read_b128 v[50:53], v21 offset:1088
	ds_read_b128 v[54:57], v21 offset:9296
	v_fmac_f32_e32 v104, v69, v83
	v_fmac_f32_e32 v104, v70, v92
	s_waitcnt lgkmcnt(3)
	v_mul_f32_e32 v74, v42, v41
	ds_read_b128 v[58:61], v21 offset:5200
	ds_read_b128 v[62:65], v21 offset:1104
	v_fmac_f32_e32 v104, v71, v93
	s_waitcnt lgkmcnt(4)
	v_fmac_f32_e32 v74, v75, v46
	v_mul_f32_e32 v75, v43, v41
	v_fmac_f32_e32 v104, v72, v94
	v_fmac_f32_e32 v75, v96, v47
	v_mul_f32_e32 v96, v44, v41
	v_fmac_f32_e32 v104, v73, v95
	v_fmac_f32_e32 v96, v84, v48
	v_mul_f32_e32 v84, v45, v41
	s_waitcnt lgkmcnt(3)
; #define LAS __attribute__((address_space(3)))
; __device__ __forceinline__ void hgrn_sample(Frame& F) {
;     ...
; #pragma unroll
;         for (int t = 0; t < 8; ++t) { float op = 0.f;
; #pragma unroll
;             for (int j4 = 0; j4 < 8; ++j4) { const f32x4 f4 = *(const LAS f32x4*)(fs + t * 128 + qd * 32 + 4 * j4), k4 = *(const LAS f32x4*)(ks + t * 128 + qd * 32 + 4 * j4), q4 = *(const LAS f32x4*)(qs + t * 128 + qd * 32 + 4 * j4);
; #pragma unroll
;                 for (int e = 0; e < 4; ++e) { float s = f4[e] * S[4 * j4 + e] + k4[e] * v[t]; S[4 * j4 + e] = s; op += q4[e] * s; } }
;             part[(qd * 8 + t) * 128 + dv] = op; }
	v_fmac_f32_e32 v104, v50, v74
	v_fmac_f32_e32 v84, v85, v49
	s_waitcnt lgkmcnt(2)
	v_mul_f32_e32 v85, v54, v41
	ds_read_b128 v[42:45], v21 offset:9312
	v_fmac_f32_e32 v104, v51, v75
	s_waitcnt lgkmcnt(2)
	v_fmac_f32_e32 v85, v86, v58
	v_mul_f32_e32 v86, v55, v41
	v_fmac_f32_e32 v104, v52, v96
	v_fmac_f32_e32 v86, v87, v59
	v_mul_f32_e32 v87, v56, v41
	v_fmac_f32_e32 v104, v53, v84
	v_fmac_f32_e32 v87, v88, v60
	v_mul_f32_e32 v88, v57, v41
	ds_read_b128 v[46:49], v21 offset:5216
	ds_read_b128 v[50:53], v21 offset:1120
	ds_read_b128 v[54:57], v21 offset:9328
	s_waitcnt lgkmcnt(4)
	v_fmac_f32_e32 v104, v62, v85
	v_fmac_f32_e32 v104, v63, v86
	v_fmac_f32_e32 v88, v89, v61
	s_waitcnt lgkmcnt(3)
	v_mul_f32_e32 v89, v42, v41
	ds_read_b128 v[58:61], v21 offset:5232
	v_fmac_f32_e32 v104, v64, v87
	s_waitcnt lgkmcnt(3)
	v_fmac_f32_e32 v89, v90, v46
	v_mul_f32_e32 v90, v43, v41
	v_fmac_f32_e32 v104, v65, v88
	v_fmac_f32_e32 v90, v91, v47
	v_mul_f32_e32 v91, v44, v41
	s_waitcnt lgkmcnt(2)
	v_fmac_f32_e32 v104, v50, v89
	v_fmac_f32_e32 v91, v97, v48
	v_mul_f32_e32 v97, v45, v41
	ds_read_b128 v[62:65], v21 offset:1136
	v_fmac_f32_e32 v104, v51, v90
	v_fmac_f32_e32 v97, v98, v49
	s_waitcnt lgkmcnt(2)
	v_mul_f32_e32 v98, v54, v41
	ds_read_b128 v[42:45], v21 offset:9728
	v_fmac_f32_e32 v104, v52, v91
	s_waitcnt lgkmcnt(2)
	v_fmac_f32_e32 v98, v99, v58
	v_mul_f32_e32 v99, v55, v41
	v_fmac_f32_e32 v104, v53, v97
	v_fmac_f32_e32 v99, v100, v59
	v_mul_f32_e32 v100, v56, v41
	v_mul_f32_e32 v41, v57, v41
	ds_read_b128 v[46:49], v21 offset:5632
	ds_read_b128 v[50:53], v21 offset:9744
	v_fmac_f32_e32 v100, v101, v60
	v_fmac_f32_e32 v41, v102, v61
	ds_read_b128 v[54:57], v21 offset:1536
	ds_read_b128 v[58:61], v21 offset:5648
	s_waitcnt lgkmcnt(5)
	v_fmac_f32_e32 v104, v62, v98
	s_waitcnt lgkmcnt(4)
	v_mul_f32_e32 v101, v42, v40
	v_fmac_f32_e32 v104, v63, v99
	s_waitcnt lgkmcnt(3)
	v_fmac_f32_e32 v101, v103, v46
	v_mul_f32_e32 v103, v43, v40
	v_fmac_f32_e32 v104, v64, v100
	s_waitcnt lgkmcnt(1)
	v_fma_f32 v102, v54, v101, 0
	v_fmac_f32_e32 v103, v105, v47
	v_mul_f32_e32 v105, v44, v40
	v_fmac_f32_e32 v104, v65, v41
	ds_read_b128 v[62:65], v21 offset:1552
	ds_read_b128 v[66:69], v21 offset:1568
	ds_read_b128 v[70:73], v21 offset:1584
	v_fmac_f32_e32 v102, v55, v103
	v_fmac_f32_e32 v105, v106, v48
	v_mul_f32_e32 v106, v45, v40
	ds_read_b128 v[42:45], v21 offset:9760
	v_fmac_f32_e32 v102, v56, v105
	v_fmac_f32_e32 v106, v107, v49
	v_mul_f32_e32 v107, v50, v40
	ds_read_b128 v[46:49], v21 offset:5664
	v_fmac_f32_e32 v102, v57, v106
	s_waitcnt lgkmcnt(5)
	v_fmac_f32_e32 v107, v76, v58
	v_mul_f32_e32 v76, v51, v40
	s_waitcnt lgkmcnt(4)
	v_fmac_f32_e32 v102, v62, v107
	v_fmac_f32_e32 v76, v77, v59
	v_mul_f32_e32 v77, v52, v40
	v_fmac_f32_e32 v102, v63, v76
	v_fmac_f32_e32 v77, v78, v60
	v_mul_f32_e32 v78, v53, v40
	ds_read_b128 v[50:53], v21 offset:9776
	v_fmac_f32_e32 v102, v64, v77
	v_fmac_f32_e32 v78, v79, v61
	s_waitcnt lgkmcnt(2)
	v_mul_f32_e32 v79, v42, v40
	ds_read_b128 v[54:57], v21 offset:5680
	v_fmac_f32_e32 v102, v65, v78
	s_waitcnt lgkmcnt(2)
	v_fmac_f32_e32 v79, v80, v46
	v_mul_f32_e32 v80, v43, v40
	v_fmac_f32_e32 v102, v66, v79
	v_fmac_f32_e32 v80, v81, v47
	v_mul_f32_e32 v81, v44, v40
	v_fmac_f32_e32 v102, v67, v80
	v_fmac_f32_e32 v81, v82, v48
	v_mul_f32_e32 v82, v45, v40
	v_fmac_f32_e32 v102, v68, v81
	v_fmac_f32_e32 v82, v83, v49
	s_waitcnt lgkmcnt(1)
	v_mul_f32_e32 v83, v50, v40
	v_fmac_f32_e32 v102, v69, v82
	s_waitcnt lgkmcnt(0)
	v_fmac_f32_e32 v83, v92, v54
	v_mul_f32_e32 v92, v51, v40
	v_fmac_f32_e32 v102, v70, v83
	v_fmac_f32_e32 v92, v93, v55
	v_mul_f32_e32 v93, v52, v40
	ds_read_b128 v[42:45], v21 offset:9792
	v_fmac_f32_e32 v102, v71, v92
	v_fmac_f32_e32 v93, v94, v56
	v_fmac_f32_e32 v102, v72, v93
	v_mul_f32_e32 v72, v53, v40
	v_fmac_f32_e32 v72, v95, v57
	ds_read_b128 v[46:49], v21 offset:5696
	ds_read_b128 v[50:53], v21 offset:1600
	ds_read_b128 v[54:57], v21 offset:9808
	ds_read_b128 v[58:61], v21 offset:5712
	ds_read_b128 v[62:65], v21 offset:1616
	v_fmac_f32_e32 v102, v73, v72
	s_waitcnt lgkmcnt(5)
	v_mul_f32_e32 v73, v42, v40
	s_waitcnt lgkmcnt(4)
	v_fmac_f32_e32 v73, v74, v46
	v_mul_f32_e32 v74, v43, v40
	s_waitcnt lgkmcnt(3)
	v_fmac_f32_e32 v102, v50, v73
	v_fmac_f32_e32 v74, v75, v47
	v_mul_f32_e32 v75, v44, v40
	v_mul_f32_e32 v94, v45, v40
	v_fmac_f32_e32 v102, v51, v74
	v_fmac_f32_e32 v75, v96, v48
	v_fmac_f32_e32 v94, v84, v49
	s_waitcnt lgkmcnt(2)
	v_mul_f32_e32 v84, v54, v40
	ds_read_b128 v[42:45], v21 offset:9824
	v_fmac_f32_e32 v102, v52, v75
	s_waitcnt lgkmcnt(2)
	v_fmac_f32_e32 v84, v85, v58
	v_mul_f32_e32 v85, v55, v40
	v_fmac_f32_e32 v102, v53, v94
	v_fmac_f32_e32 v85, v86, v59
	v_mul_f32_e32 v86, v56, v40
	s_waitcnt lgkmcnt(1)
	v_fmac_f32_e32 v102, v62, v84
	v_fmac_f32_e32 v86, v87, v60
	v_mul_f32_e32 v87, v57, v40
	ds_read_b128 v[46:49], v21 offset:5728
	ds_read_b128 v[50:53], v21 offset:1632
	ds_read_b128 v[54:57], v21 offset:9840
	v_fmac_f32_e32 v102, v63, v85
	v_fmac_f32_e32 v102, v64, v86
	v_fmac_f32_e32 v87, v88, v61
	s_waitcnt lgkmcnt(3)
	v_mul_f32_e32 v88, v42, v40
	ds_read_b128 v[58:61], v21 offset:5744
	v_fmac_f32_e32 v102, v65, v87
	s_waitcnt lgkmcnt(3)
	v_fmac_f32_e32 v88, v89, v46
	ds_read_b128 v[62:65], v21 offset:1648
	v_mul_f32_e32 v89, v43, v40
	s_waitcnt lgkmcnt(3)
	v_fmac_f32_e32 v102, v50, v88
	v_fmac_f32_e32 v89, v90, v47
	v_mul_f32_e32 v90, v44, v40
	v_fmac_f32_e32 v102, v51, v89
	v_fmac_f32_e32 v90, v91, v48
	v_mul_f32_e32 v91, v45, v40
	v_fmac_f32_e32 v102, v52, v90
	v_fmac_f32_e32 v91, v97, v49
	s_waitcnt lgkmcnt(2)
	v_mul_f32_e32 v95, v54, v40
	v_fmac_f32_e32 v102, v53, v91
	s_waitcnt lgkmcnt(1)
; #define LAS __attribute__((address_space(3)))
; __device__ __forceinline__ void hgrn_sample(Frame& F) {
;     ...
; #pragma unroll
;         for (int t = 0; t < 8; ++t) { float op = 0.f;
; #pragma unroll
;             for (int j4 = 0; j4 < 8; ++j4) { const f32x4 f4 = *(const LAS f32x4*)(fs + t * 128 + qd * 32 + 4 * j4), k4 = *(const LAS f32x4*)(ks + t * 128 + qd * 32 + 4 * j4), q4 = *(const LAS f32x4*)(qs + t * 128 + qd * 32 + 4 * j4);
; #pragma unroll
;                 for (int e = 0; e < 4; ++e) { float s = f4[e] * S[4 * j4 + e] + k4[e] * v[t]; S[4 * j4 + e] = s; op += q4[e] * s; } }
;             part[(qd * 8 + t) * 128 + dv] = op; }
	v_fmac_f32_e32 v95, v98, v58
	v_mul_f32_e32 v96, v55, v40
	s_waitcnt lgkmcnt(0)
	v_fmac_f32_e32 v102, v62, v95
	v_fmac_f32_e32 v96, v99, v59
	v_mul_f32_e32 v97, v56, v40
	v_fmac_f32_e32 v102, v63, v96
	v_fmac_f32_e32 v97, v100, v60
	v_mul_f32_e32 v98, v57, v40
	v_fmac_f32_e32 v102, v64, v97
	v_fmac_f32_e32 v98, v41, v61
	ds_read_b128 v[40:43], v21 offset:10240
	v_fmac_f32_e32 v102, v65, v98
	ds_write2st64_b32 v32, v104, v102 offset0:52 offset1:54
	ds_read_b128 v[44:47], v21 offset:6144
	ds_read_b128 v[48:51], v21 offset:10256
	ds_read_b128 v[52:55], v21 offset:2048
	ds_read_b128 v[56:59], v21 offset:6160
	s_waitcnt lgkmcnt(5)
	v_mul_f32_e32 v99, v40, v39
	ds_read_b128 v[60:63], v21 offset:2064
	ds_read_b128 v[64:67], v21 offset:2080
	ds_read_b128 v[68:71], v21 offset:2096
	s_waitcnt lgkmcnt(6)
	v_fmac_f32_e32 v99, v101, v44
	v_mul_f32_e32 v101, v41, v39
	v_fmac_f32_e32 v101, v103, v45
	v_mul_f32_e32 v102, v42, v39
	v_mul_f32_e32 v103, v43, v39
	ds_read_b128 v[40:43], v21 offset:10272
	v_fmac_f32_e32 v102, v105, v46
	v_fmac_f32_e32 v103, v106, v47
	ds_read_b128 v[44:47], v21 offset:6176
	s_waitcnt lgkmcnt(6)
	v_fma_f32 v100, v52, v99, 0
	v_mul_f32_e32 v105, v49, v39
	v_fmac_f32_e32 v100, v53, v101
	s_waitcnt lgkmcnt(5)
	v_fmac_f32_e32 v105, v76, v57
	v_mul_f32_e32 v76, v50, v39
	v_fmac_f32_e32 v100, v54, v102
	v_mul_f32_e32 v104, v48, v39
	v_fmac_f32_e32 v76, v77, v58
	v_mul_f32_e32 v77, v51, v39
	ds_read_b128 v[48:51], v21 offset:10288
	v_fmac_f32_e32 v100, v55, v103
	v_fmac_f32_e32 v77, v78, v59
	s_waitcnt lgkmcnt(2)
	v_mul_f32_e32 v78, v40, v39
	ds_read_b128 v[52:55], v21 offset:6192
	v_fmac_f32_e32 v104, v107, v56
	s_waitcnt lgkmcnt(2)
	v_fmac_f32_e32 v78, v79, v44
	v_mul_f32_e32 v79, v41, v39
	v_fmac_f32_e32 v100, v60, v104
	v_fmac_f32_e32 v79, v80, v45
	v_mul_f32_e32 v80, v42, v39
	v_fmac_f32_e32 v100, v61, v105
	v_fmac_f32_e32 v80, v81, v46
	v_mul_f32_e32 v81, v43, v39
	v_fmac_f32_e32 v100, v62, v76
	v_fmac_f32_e32 v81, v82, v47
	s_waitcnt lgkmcnt(1)
	v_mul_f32_e32 v82, v48, v39
	v_fmac_f32_e32 v100, v63, v77
	s_waitcnt lgkmcnt(0)
	v_fmac_f32_e32 v82, v83, v52
	v_mul_f32_e32 v83, v49, v39
	ds_read_b128 v[40:43], v21 offset:10304
	v_fmac_f32_e32 v100, v64, v78
	v_fmac_f32_e32 v83, v92, v53
	v_mul_f32_e32 v92, v50, v39
	v_fmac_f32_e32 v100, v65, v79
	v_fmac_f32_e32 v92, v93, v54
	v_mul_f32_e32 v93, v51, v39
	v_fmac_f32_e32 v100, v66, v80
	v_fmac_f32_e32 v93, v72, v55
	ds_read_b128 v[44:47], v21 offset:6208
	ds_read_b128 v[48:51], v21 offset:2112
	ds_read_b128 v[52:55], v21 offset:10320
	v_fmac_f32_e32 v100, v67, v81
	v_fmac_f32_e32 v100, v68, v82
	s_waitcnt lgkmcnt(3)
	v_mul_f32_e32 v72, v40, v39
	ds_read_b128 v[56:59], v21 offset:6224
	ds_read_b128 v[60:63], v21 offset:2128
	v_fmac_f32_e32 v100, v69, v83
	s_waitcnt lgkmcnt(4)
	v_fmac_f32_e32 v72, v73, v44
	v_mul_f32_e32 v73, v41, v39
	v_fmac_f32_e32 v100, v70, v92
	v_fmac_f32_e32 v73, v74, v45
	v_mul_f32_e32 v74, v42, v39
	v_fmac_f32_e32 v100, v71, v93
	v_fmac_f32_e32 v74, v75, v46
	v_mul_f32_e32 v75, v43, v39
	s_waitcnt lgkmcnt(3)
	v_fmac_f32_e32 v100, v48, v72
	v_fmac_f32_e32 v75, v94, v47
	s_waitcnt lgkmcnt(2)
	v_mul_f32_e32 v94, v52, v39
	ds_read_b128 v[40:43], v21 offset:10336
	v_fmac_f32_e32 v100, v49, v73
	s_waitcnt lgkmcnt(2)
	v_fmac_f32_e32 v94, v84, v56
	v_mul_f32_e32 v84, v53, v39
	v_fmac_f32_e32 v100, v50, v74
	v_fmac_f32_e32 v84, v85, v57
	v_mul_f32_e32 v85, v54, v39
	v_fmac_f32_e32 v100, v51, v75
	v_fmac_f32_e32 v85, v86, v58
	v_mul_f32_e32 v86, v55, v39
	ds_read_b128 v[44:47], v21 offset:6240
	ds_read_b128 v[48:51], v21 offset:2144
	ds_read_b128 v[52:55], v21 offset:10352
	s_waitcnt lgkmcnt(4)
	v_fmac_f32_e32 v100, v60, v94
	v_fmac_f32_e32 v100, v61, v84
	v_fmac_f32_e32 v86, v87, v59
	s_waitcnt lgkmcnt(3)
	v_mul_f32_e32 v87, v40, v39
	ds_read_b128 v[56:59], v21 offset:6256
	v_fmac_f32_e32 v100, v62, v85
	s_waitcnt lgkmcnt(3)
	v_fmac_f32_e32 v87, v88, v44
	v_mul_f32_e32 v88, v41, v39
	v_fmac_f32_e32 v100, v63, v86
	v_fmac_f32_e32 v88, v89, v45
	v_mul_f32_e32 v89, v42, v39
	s_waitcnt lgkmcnt(2)
	v_fmac_f32_e32 v100, v48, v87
	v_fmac_f32_e32 v89, v90, v46
	v_mul_f32_e32 v90, v43, v39
	ds_read_b128 v[60:63], v21 offset:2160
	v_fmac_f32_e32 v100, v49, v88
	v_fmac_f32_e32 v90, v91, v47
	s_waitcnt lgkmcnt(2)
	v_mul_f32_e32 v91, v52, v39
	ds_read_b128 v[40:43], v21 offset:10752
	v_fmac_f32_e32 v100, v50, v89
	s_waitcnt lgkmcnt(2)
	v_fmac_f32_e32 v91, v95, v56
	v_mul_f32_e32 v95, v53, v39
	v_fmac_f32_e32 v100, v51, v90
	v_fmac_f32_e32 v95, v96, v57
	v_mul_f32_e32 v96, v54, v39
	v_mul_f32_e32 v39, v55, v39
	ds_read_b128 v[44:47], v21 offset:6656
	ds_read_b128 v[48:51], v21 offset:10768
	v_fmac_f32_e32 v96, v97, v58
	v_fmac_f32_e32 v39, v98, v59
	ds_read_b128 v[52:55], v21 offset:2560
	ds_read_b128 v[56:59], v21 offset:6672
	s_waitcnt lgkmcnt(5)
	v_fmac_f32_e32 v100, v60, v91
	s_waitcnt lgkmcnt(4)
	v_mul_f32_e32 v97, v40, v38
	v_fmac_f32_e32 v100, v61, v95
	s_waitcnt lgkmcnt(3)
	v_fmac_f32_e32 v97, v99, v44
	v_mul_f32_e32 v99, v41, v38
	v_fmac_f32_e32 v100, v62, v96
	s_waitcnt lgkmcnt(1)
	v_fma_f32 v98, v52, v97, 0
	v_fmac_f32_e32 v99, v101, v45
	v_mul_f32_e32 v101, v42, v38
	v_fmac_f32_e32 v100, v63, v39
	ds_read_b128 v[60:63], v21 offset:2576
	ds_read_b128 v[64:67], v21 offset:2592
	ds_read_b128 v[68:71], v21 offset:2608
	v_fmac_f32_e32 v98, v53, v99
	v_fmac_f32_e32 v101, v102, v46
	v_mul_f32_e32 v102, v43, v38
	ds_read_b128 v[40:43], v21 offset:10784
	v_fmac_f32_e32 v98, v54, v101
	v_fmac_f32_e32 v102, v103, v47
	v_mul_f32_e32 v103, v48, v38
	ds_read_b128 v[44:47], v21 offset:6688
	v_fmac_f32_e32 v98, v55, v102
	s_waitcnt lgkmcnt(5)
; #define LAS __attribute__((address_space(3)))
; __device__ __forceinline__ void hgrn_sample(Frame& F) {
;     ...
;         for (int t = 0; t < 8; ++t) { float op = 0.f;
; #pragma unroll
;             for (int j4 = 0; j4 < 8; ++j4) { const f32x4 f4 = *(const LAS f32x4*)(fs + t * 128 + qd * 32 + 4 * j4), k4 = *(const LAS f32x4*)(ks + t * 128 + qd * 32 + 4 * j4), q4 = *(const LAS f32x4*)(qs + t * 128 + qd * 32 + 4 * j4);
; #pragma unroll
;                 for (int e = 0; e < 4; ++e) { float s = f4[e] * S[4 * j4 + e] + k4[e] * v[t]; S[4 * j4 + e] = s; op += q4[e] * s; } }
;             part[(qd * 8 + t) * 128 + dv] = op; }
	v_fmac_f32_e32 v103, v104, v56
	v_mul_f32_e32 v104, v49, v38
	s_waitcnt lgkmcnt(4)
	v_fmac_f32_e32 v98, v60, v103
	v_fmac_f32_e32 v104, v105, v57
	v_mul_f32_e32 v105, v50, v38
	v_fmac_f32_e32 v98, v61, v104
	v_fmac_f32_e32 v105, v76, v58
	v_mul_f32_e32 v76, v51, v38
	ds_read_b128 v[48:51], v21 offset:10800
	v_fmac_f32_e32 v98, v62, v105
	v_fmac_f32_e32 v76, v77, v59
	s_waitcnt lgkmcnt(2)
	v_mul_f32_e32 v77, v40, v38
	ds_read_b128 v[52:55], v21 offset:6704
	v_fmac_f32_e32 v98, v63, v76
	s_waitcnt lgkmcnt(2)
	v_fmac_f32_e32 v77, v78, v44
	v_mul_f32_e32 v78, v41, v38
	v_fmac_f32_e32 v98, v64, v77
	v_fmac_f32_e32 v78, v79, v45
	v_mul_f32_e32 v79, v42, v38
	v_fmac_f32_e32 v98, v65, v78
	v_fmac_f32_e32 v79, v80, v46
	v_mul_f32_e32 v80, v43, v38
	v_fmac_f32_e32 v98, v66, v79
	v_fmac_f32_e32 v80, v81, v47
	s_waitcnt lgkmcnt(1)
	v_mul_f32_e32 v81, v48, v38
	v_fmac_f32_e32 v98, v67, v80
	s_waitcnt lgkmcnt(0)
	v_fmac_f32_e32 v81, v82, v52
	v_mul_f32_e32 v82, v49, v38
	v_fmac_f32_e32 v98, v68, v81
	v_fmac_f32_e32 v82, v83, v53
	v_mul_f32_e32 v83, v50, v38
	ds_read_b128 v[40:43], v21 offset:10816
	v_fmac_f32_e32 v98, v69, v82
	v_fmac_f32_e32 v83, v92, v54
	v_fmac_f32_e32 v98, v70, v83
	v_mul_f32_e32 v70, v51, v38
	v_fmac_f32_e32 v70, v93, v55
	ds_read_b128 v[44:47], v21 offset:6720
	ds_read_b128 v[48:51], v21 offset:2624
	ds_read_b128 v[52:55], v21 offset:10832
	v_fmac_f32_e32 v98, v71, v70
	s_waitcnt lgkmcnt(3)
	v_mul_f32_e32 v71, v40, v38
	ds_read_b128 v[56:59], v21 offset:6736
	ds_read_b128 v[60:63], v21 offset:2640
	s_waitcnt lgkmcnt(4)
	v_fmac_f32_e32 v71, v72, v44
	v_mul_f32_e32 v72, v41, v38
	s_waitcnt lgkmcnt(3)
	v_fmac_f32_e32 v98, v48, v71
	v_fmac_f32_e32 v72, v73, v45
	v_mul_f32_e32 v73, v42, v38
	v_fmac_f32_e32 v98, v49, v72
	v_fmac_f32_e32 v73, v74, v46
	v_mul_f32_e32 v74, v43, v38
	ds_read_b128 v[40:43], v21 offset:10848
	v_fmac_f32_e32 v98, v50, v73
	v_fmac_f32_e32 v74, v75, v47
	s_waitcnt lgkmcnt(3)
	v_mul_f32_e32 v75, v52, v38
	v_mul_f32_e32 v92, v53, v38
	v_fmac_f32_e32 v98, v51, v74
	s_waitcnt lgkmcnt(2)
	v_fmac_f32_e32 v75, v94, v56
	v_fmac_f32_e32 v92, v84, v57
	v_mul_f32_e32 v84, v54, v38
	s_waitcnt lgkmcnt(1)
	v_fmac_f32_e32 v98, v60, v75
	v_fmac_f32_e32 v84, v85, v58
	v_mul_f32_e32 v85, v55, v38
	ds_read_b128 v[44:47], v21 offset:6752
	ds_read_b128 v[48:51], v21 offset:2656
	ds_read_b128 v[52:55], v21 offset:10864
	v_fmac_f32_e32 v98, v61, v92
	v_fmac_f32_e32 v98, v62, v84
	v_fmac_f32_e32 v85, v86, v59
	s_waitcnt lgkmcnt(3)
	v_mul_f32_e32 v86, v40, v38
	ds_read_b128 v[56:59], v21 offset:6768
	v_fmac_f32_e32 v98, v63, v85
	s_waitcnt lgkmcnt(3)
	v_fmac_f32_e32 v86, v87, v44
	ds_read_b128 v[60:63], v21 offset:2672
	v_mul_f32_e32 v87, v41, v38
	s_waitcnt lgkmcnt(3)
	v_fmac_f32_e32 v98, v48, v86
	v_fmac_f32_e32 v87, v88, v45
	v_mul_f32_e32 v88, v42, v38
	v_fmac_f32_e32 v98, v49, v87
	v_fmac_f32_e32 v88, v89, v46
	v_mul_f32_e32 v89, v43, v38
	v_fmac_f32_e32 v98, v50, v88
	v_fmac_f32_e32 v89, v90, v47
	s_waitcnt lgkmcnt(2)
	v_mul_f32_e32 v90, v52, v38
	v_fmac_f32_e32 v98, v51, v89
	s_waitcnt lgkmcnt(1)
	v_fmac_f32_e32 v90, v91, v56
	v_mul_f32_e32 v91, v53, v38
	s_waitcnt lgkmcnt(0)
	v_fmac_f32_e32 v98, v60, v90
	v_fmac_f32_e32 v91, v95, v57
	v_mul_f32_e32 v93, v54, v38
	v_fmac_f32_e32 v98, v61, v91
	v_fmac_f32_e32 v93, v96, v58
	v_mul_f32_e32 v94, v55, v38
	v_fmac_f32_e32 v98, v62, v93
	v_fmac_f32_e32 v94, v39, v59
	ds_read_b128 v[38:41], v21 offset:11264
	v_fmac_f32_e32 v98, v63, v94
	ds_write2st64_b32 v32, v100, v98 offset0:56 offset1:58
	ds_read_b128 v[42:45], v21 offset:7168
	ds_read_b128 v[46:49], v21 offset:11280
	ds_read_b128 v[50:53], v21 offset:3072
	ds_read_b128 v[54:57], v21 offset:7184
	s_waitcnt lgkmcnt(5)
	v_mul_f32_e32 v95, v38, v37
	ds_read_b128 v[58:61], v21 offset:3088
	ds_read_b128 v[62:65], v21 offset:3104
	ds_read_b128 v[66:69], v21 offset:3120
	s_waitcnt lgkmcnt(6)
	v_fmac_f32_e32 v95, v97, v42
	v_mul_f32_e32 v97, v39, v37
	v_fmac_f32_e32 v97, v99, v43
	v_mul_f32_e32 v98, v40, v37
	v_mul_f32_e32 v99, v41, v37
	ds_read_b128 v[38:41], v21 offset:11296
	v_fmac_f32_e32 v98, v101, v44
	v_fmac_f32_e32 v99, v102, v45
	ds_read_b128 v[42:45], v21 offset:7200
	s_waitcnt lgkmcnt(6)
	v_fma_f32 v96, v50, v95, 0
	v_fmac_f32_e32 v96, v51, v97
	v_mul_f32_e32 v100, v46, v37
	v_fmac_f32_e32 v96, v52, v98
	s_waitcnt lgkmcnt(5)
	v_fmac_f32_e32 v100, v103, v54
	v_mul_f32_e32 v101, v47, v37
	v_mul_f32_e32 v102, v48, v37
	v_mul_f32_e32 v103, v49, v37
	ds_read_b128 v[46:49], v21 offset:11312
	v_fmac_f32_e32 v96, v53, v99
	v_fmac_f32_e32 v103, v76, v57
	s_waitcnt lgkmcnt(2)
	v_mul_f32_e32 v76, v38, v37
	ds_read_b128 v[50:53], v21 offset:7216
	s_waitcnt lgkmcnt(2)
	v_fmac_f32_e32 v76, v77, v42
	v_mul_f32_e32 v77, v39, v37
	v_fmac_f32_e32 v96, v58, v100
	v_fmac_f32_e32 v101, v104, v55
	v_fmac_f32_e32 v77, v78, v43
	v_mul_f32_e32 v78, v40, v37
	v_fmac_f32_e32 v96, v59, v101
	v_fmac_f32_e32 v102, v105, v56
	v_fmac_f32_e32 v78, v79, v44
	v_mul_f32_e32 v79, v41, v37
	v_fmac_f32_e32 v96, v60, v102
	v_fmac_f32_e32 v79, v80, v45
	s_waitcnt lgkmcnt(1)
	v_mul_f32_e32 v80, v46, v37
	v_fmac_f32_e32 v96, v61, v103
	s_waitcnt lgkmcnt(0)
	v_fmac_f32_e32 v80, v81, v50
	v_mul_f32_e32 v81, v47, v37
	ds_read_b128 v[38:41], v21 offset:11328
	v_fmac_f32_e32 v96, v62, v76
	v_fmac_f32_e32 v81, v82, v51
	v_mul_f32_e32 v82, v48, v37
	v_fmac_f32_e32 v96, v63, v77
	v_fmac_f32_e32 v82, v83, v52
	v_mul_f32_e32 v83, v49, v37
	v_fmac_f32_e32 v96, v64, v78
	v_fmac_f32_e32 v83, v70, v53
	ds_read_b128 v[42:45], v21 offset:7232
	ds_read_b128 v[46:49], v21 offset:3136
	ds_read_b128 v[50:53], v21 offset:11344
	v_fmac_f32_e32 v96, v65, v79
	v_fmac_f32_e32 v96, v66, v80
	s_waitcnt lgkmcnt(3)
; #define LAS __attribute__((address_space(3)))
; __device__ __forceinline__ void hgrn_sample(Frame& F) {
;     ...
;         for (int t = 0; t < 8; ++t) { float op = 0.f;
; #pragma unroll
;             for (int j4 = 0; j4 < 8; ++j4) { const f32x4 f4 = *(const LAS f32x4*)(fs + t * 128 + qd * 32 + 4 * j4), k4 = *(const LAS f32x4*)(ks + t * 128 + qd * 32 + 4 * j4), q4 = *(const LAS f32x4*)(qs + t * 128 + qd * 32 + 4 * j4);
; #pragma unroll
;                 for (int e = 0; e < 4; ++e) { float s = f4[e] * S[4 * j4 + e] + k4[e] * v[t]; S[4 * j4 + e] = s; op += q4[e] * s; } }
;             part[(qd * 8 + t) * 128 + dv] = op; }
	v_mul_f32_e32 v70, v38, v37
	ds_read_b128 v[54:57], v21 offset:7248
	ds_read_b128 v[58:61], v21 offset:3152
	v_fmac_f32_e32 v96, v67, v81
	s_waitcnt lgkmcnt(4)
	v_fmac_f32_e32 v70, v71, v42
	v_mul_f32_e32 v71, v39, v37
	v_fmac_f32_e32 v96, v68, v82
	v_fmac_f32_e32 v71, v72, v43
	v_mul_f32_e32 v72, v40, v37
	v_fmac_f32_e32 v96, v69, v83
	v_fmac_f32_e32 v72, v73, v44
	v_mul_f32_e32 v73, v41, v37
	s_waitcnt lgkmcnt(3)
	v_fmac_f32_e32 v96, v46, v70
	v_fmac_f32_e32 v73, v74, v45
	s_waitcnt lgkmcnt(2)
	v_mul_f32_e32 v74, v50, v37
	ds_read_b128 v[38:41], v21 offset:11360
	v_fmac_f32_e32 v96, v47, v71
	s_waitcnt lgkmcnt(2)
	v_fmac_f32_e32 v74, v75, v54
	v_mul_f32_e32 v75, v51, v37
	v_fmac_f32_e32 v96, v48, v72
	v_fmac_f32_e32 v75, v92, v55
	v_mul_f32_e32 v92, v52, v37
	v_fmac_f32_e32 v96, v49, v73
	v_fmac_f32_e32 v92, v84, v56
	v_mul_f32_e32 v84, v53, v37
	ds_read_b128 v[42:45], v21 offset:7264
	ds_read_b128 v[46:49], v21 offset:3168
	ds_read_b128 v[50:53], v21 offset:11376
	s_waitcnt lgkmcnt(4)
	v_fmac_f32_e32 v96, v58, v74
	v_fmac_f32_e32 v96, v59, v75
	v_fmac_f32_e32 v84, v85, v57
	s_waitcnt lgkmcnt(3)
	v_mul_f32_e32 v85, v38, v37
	ds_read_b128 v[54:57], v21 offset:7280
	v_fmac_f32_e32 v96, v60, v92
	s_waitcnt lgkmcnt(3)
	v_fmac_f32_e32 v85, v86, v42
	v_mul_f32_e32 v86, v39, v37
	v_fmac_f32_e32 v96, v61, v84
	v_fmac_f32_e32 v86, v87, v43
	v_mul_f32_e32 v87, v40, v37
	s_waitcnt lgkmcnt(2)
	v_fmac_f32_e32 v96, v46, v85
	v_fmac_f32_e32 v87, v88, v44
	v_mul_f32_e32 v88, v41, v37
	ds_read_b128 v[58:61], v21 offset:3184
	v_fmac_f32_e32 v96, v47, v86
	v_fmac_f32_e32 v88, v89, v45
	s_waitcnt lgkmcnt(2)
	v_mul_f32_e32 v89, v50, v37
	ds_read_b128 v[38:41], v21 offset:11776
	v_fmac_f32_e32 v96, v48, v87
	s_waitcnt lgkmcnt(2)
	v_fmac_f32_e32 v89, v90, v54
	v_mul_f32_e32 v90, v51, v37
	v_fmac_f32_e32 v96, v49, v88
	v_fmac_f32_e32 v90, v91, v55
	v_mul_f32_e32 v91, v52, v37
	v_mul_f32_e32 v37, v53, v37
	ds_read_b128 v[42:45], v21 offset:7680
	ds_read_b128 v[46:49], v21 offset:11792
	v_fmac_f32_e32 v91, v93, v56
	v_fmac_f32_e32 v37, v94, v57
	ds_read_b128 v[50:53], v21 offset:3584
	ds_read_b128 v[54:57], v21 offset:7696
	s_waitcnt lgkmcnt(5)
	v_fmac_f32_e32 v96, v58, v89
	s_waitcnt lgkmcnt(4)
	v_mul_f32_e32 v93, v38, v36
	v_fmac_f32_e32 v96, v59, v90
	s_waitcnt lgkmcnt(3)
	v_fmac_f32_e32 v93, v95, v42
	v_mul_f32_e32 v95, v39, v36
	v_fmac_f32_e32 v96, v60, v91
	s_waitcnt lgkmcnt(1)
	v_fma_f32 v94, v50, v93, 0
	v_fmac_f32_e32 v95, v97, v43
	v_mul_f32_e32 v97, v40, v36
	v_fmac_f32_e32 v96, v61, v37
	ds_read_b128 v[58:61], v21 offset:3600
	ds_read_b128 v[62:65], v21 offset:3616
	ds_read_b128 v[66:69], v21 offset:3632
	v_fmac_f32_e32 v94, v51, v95
	v_fmac_f32_e32 v97, v98, v44
	v_mul_f32_e32 v98, v41, v36
	ds_read_b128 v[38:41], v21 offset:11808
	v_fmac_f32_e32 v94, v52, v97
	v_fmac_f32_e32 v98, v99, v45
	v_mul_f32_e32 v99, v46, v36
	ds_read_b128 v[42:45], v21 offset:7712
	v_fmac_f32_e32 v94, v53, v98
	s_waitcnt lgkmcnt(5)
	v_fmac_f32_e32 v99, v100, v54
	v_mul_f32_e32 v100, v47, v36
	s_waitcnt lgkmcnt(4)
	v_fmac_f32_e32 v94, v58, v99
	v_fmac_f32_e32 v100, v101, v55
	v_mul_f32_e32 v101, v48, v36
	v_fmac_f32_e32 v94, v59, v100
	v_fmac_f32_e32 v101, v102, v56
	v_mul_f32_e32 v102, v49, v36
	v_fmac_f32_e32 v94, v60, v101
	v_fmac_f32_e32 v102, v103, v57
	ds_read_b128 v[46:49], v21 offset:11824
	s_waitcnt lgkmcnt(2)
	v_mul_f32_e32 v103, v38, v36
	v_fmac_f32_e32 v94, v61, v102
	ds_read_b128 v[50:53], v21 offset:7728
	s_waitcnt lgkmcnt(2)
	v_fmac_f32_e32 v103, v76, v42
	v_fmac_f32_e32 v94, v62, v103
	v_mul_f32_e32 v62, v39, v36
	v_fmac_f32_e32 v62, v77, v43
	v_fmac_f32_e32 v94, v63, v62
	v_mul_f32_e32 v63, v40, v36
	v_fmac_f32_e32 v63, v78, v44
	v_fmac_f32_e32 v94, v64, v63
	v_mul_f32_e32 v64, v41, v36
	v_fmac_f32_e32 v64, v79, v45
	v_fmac_f32_e32 v94, v65, v64
	s_waitcnt lgkmcnt(1)
	v_mul_f32_e32 v65, v46, v36
	s_waitcnt lgkmcnt(0)
	v_fmac_f32_e32 v65, v80, v50
	v_fmac_f32_e32 v94, v66, v65
	v_mul_f32_e32 v66, v47, v36
	v_fmac_f32_e32 v66, v81, v51
	v_fmac_f32_e32 v94, v67, v66
	v_mul_f32_e32 v67, v48, v36
	ds_read_b128 v[38:41], v21 offset:11840
	v_fmac_f32_e32 v67, v82, v52
	v_fmac_f32_e32 v94, v68, v67
	v_mul_f32_e32 v68, v49, v36
	v_fmac_f32_e32 v68, v83, v53
	ds_read_b128 v[42:45], v21 offset:7744
	ds_read_b128 v[46:49], v21 offset:3648
	ds_read_b128 v[50:53], v21 offset:11856
	v_fmac_f32_e32 v94, v69, v68
	s_waitcnt lgkmcnt(3)
	v_mul_f32_e32 v69, v38, v36
	ds_read_b128 v[54:57], v21 offset:7760
	ds_read_b128 v[58:61], v21 offset:3664
	s_waitcnt lgkmcnt(4)
	v_fmac_f32_e32 v69, v70, v42
	v_mul_f32_e32 v70, v39, v36
	s_waitcnt lgkmcnt(3)
; #define LAS __attribute__((address_space(3)))
; __device__ __forceinline__ void hgrn_sample(Frame& F) {
;     ...
;         for (int t = 0; t < 8; ++t) { float op = 0.f;
; #pragma unroll
;             for (int j4 = 0; j4 < 8; ++j4) { const f32x4 f4 = *(const LAS f32x4*)(fs + t * 128 + qd * 32 + 4 * j4), k4 = *(const LAS f32x4*)(ks + t * 128 + qd * 32 + 4 * j4), q4 = *(const LAS f32x4*)(qs + t * 128 + qd * 32 + 4 * j4);
; #pragma unroll
;                 for (int e = 0; e < 4; ++e) { float s = f4[e] * S[4 * j4 + e] + k4[e] * v[t]; S[4 * j4 + e] = s; op += q4[e] * s; } }
;             part[(qd * 8 + t) * 128 + dv] = op; }
;         float* so = F.o_hgrn_s + ((size_t)b * 4 + h) * 128 * 128;
; #pragma unroll
;         for (int j = 0; j < 32; ++j) so[(size_t)(qd * 32 + j) * 128 + dv] = S[j];
;         __syncthreads();
;         float o2[2];
; #pragma unroll
;         for (int i = 0; i < 2; ++i) { const int idx = tid + 512 * i, t = idx >> 7, d2 = idx & 127;
;             const float o = (part[(0 * 8 + t) * 128 + d2] + part[(1 * 8 + t) * 128 + d2]) + (part[(2 * 8 + t) * 128 + d2] + part[(3 * 8 + t) * 128 + d2]);
;             o2[i] = o; const float ssq = wave_sum(o * o); if (F.lane == 0) red[i * 8 + F.wave] = ssq; }
	v_fmac_f32_e32 v94, v46, v69
	v_fmac_f32_e32 v70, v71, v43
	v_mul_f32_e32 v71, v40, v36
	v_fmac_f32_e32 v94, v47, v70
	v_fmac_f32_e32 v71, v72, v44
	v_mul_f32_e32 v72, v41, v36
	ds_read_b128 v[38:41], v21 offset:11872
	v_fmac_f32_e32 v94, v48, v71
	v_fmac_f32_e32 v72, v73, v45
	s_waitcnt lgkmcnt(3)
	v_mul_f32_e32 v73, v50, v36
	v_fmac_f32_e32 v94, v49, v72
	s_waitcnt lgkmcnt(2)
	v_fmac_f32_e32 v73, v74, v54
	v_mul_f32_e32 v74, v51, v36
	s_waitcnt lgkmcnt(1)
	v_fmac_f32_e32 v94, v58, v73
	v_fmac_f32_e32 v74, v75, v55
	v_mul_f32_e32 v75, v52, v36
	v_mul_f32_e32 v76, v53, v36
	ds_read_b128 v[42:45], v21 offset:7776
	ds_read_b128 v[46:49], v21 offset:3680
	ds_read_b128 v[50:53], v21 offset:11888
	v_fmac_f32_e32 v94, v59, v74
	v_fmac_f32_e32 v75, v92, v56
	v_fmac_f32_e32 v94, v60, v75
	v_fmac_f32_e32 v76, v84, v57
	s_waitcnt lgkmcnt(3)
	v_mul_f32_e32 v77, v38, v36
	ds_read_b128 v[54:57], v21 offset:7792
	v_fmac_f32_e32 v94, v61, v76
	s_waitcnt lgkmcnt(3)
	v_fmac_f32_e32 v77, v85, v42
	v_mul_f32_e32 v42, v39, v36
	ds_read_b128 v[58:61], v21 offset:3696
	s_waitcnt lgkmcnt(3)
	v_fmac_f32_e32 v94, v46, v77
	v_fmac_f32_e32 v42, v86, v43
	v_mul_f32_e32 v43, v40, v36
	s_lshl_b32 s4, s14, 16
	v_fmac_f32_e32 v94, v47, v42
	v_fmac_f32_e32 v43, v87, v44
	s_add_u32 s0, s0, s4
	v_fmac_f32_e32 v94, v48, v43
	v_mul_f32_e32 v44, v41, v36
	s_waitcnt lgkmcnt(2)
	v_mul_f32_e32 v48, v53, v36
	s_addc_u32 s1, s1, 0
	v_fmac_f32_e32 v44, v88, v45
	v_mul_f32_e32 v45, v50, v36
	v_mul_f32_e32 v46, v51, v36
	v_mul_f32_e32 v47, v52, v36
	s_waitcnt lgkmcnt(1)
	v_fmac_f32_e32 v48, v37, v57
	v_lshl_add_u64 v[36:37], s[0:1], 0, v[14:15]
	v_fmac_f32_e32 v94, v49, v44
	v_fmac_f32_e32 v45, v89, v54
	v_lshl_add_u64 v[36:37], v[36:37], 0, v[6:7]
	s_waitcnt lgkmcnt(0)
	v_fmac_f32_e32 v94, v58, v45
	v_fmac_f32_e32 v46, v90, v55
	v_add_co_u32_e64 v38, s[0:1], s9, v36
	v_fmac_f32_e32 v94, v59, v46
	v_fmac_f32_e32 v47, v91, v56
	v_addc_co_u32_e64 v39, s[0:1], 0, v37, s[0:1]
	v_fmac_f32_e32 v94, v60, v47
	v_add_co_u32_e64 v40, s[0:1], s10, v36
	v_fmac_f32_e32 v94, v61, v48
	s_nop 0
	v_addc_co_u32_e64 v41, s[0:1], 0, v37, s[0:1]
	ds_write2st64_b32 v32, v96, v94 offset0:60 offset1:62
	global_store_dword v[36:37], v93, off
	global_store_dword v[36:37], v95, off offset:512
	global_store_dword v[36:37], v97, off offset:1024
	global_store_dword v[36:37], v98, off offset:1536
	global_store_dword v[36:37], v99, off offset:2048
	global_store_dword v[36:37], v100, off offset:2560
	global_store_dword v[36:37], v101, off offset:3072
	global_store_dword v[36:37], v102, off offset:3584
	v_add_co_u32_e64 v36, s[0:1], s11, v36
	global_store_dword v[40:41], v103, off offset:-4096
	global_store_dword v[38:39], v62, off offset:512
	global_store_dword v[38:39], v63, off offset:1024
	global_store_dword v[38:39], v64, off offset:1536
	global_store_dword v[38:39], v65, off offset:2048
	global_store_dword v[38:39], v66, off offset:2560
	global_store_dword v[38:39], v67, off offset:3072
	global_store_dword v[38:39], v68, off offset:3584
	global_store_dword v[40:41], v69, off
	global_store_dword v[40:41], v70, off offset:512
	global_store_dword v[40:41], v71, off offset:1024
	global_store_dword v[40:41], v72, off offset:1536
	global_store_dword v[40:41], v73, off offset:2048
	global_store_dword v[40:41], v74, off offset:2560
	global_store_dword v[40:41], v75, off offset:3072
	global_store_dword v[40:41], v76, off offset:3584
	v_addc_co_u32_e64 v37, s[0:1], 0, v37, s[0:1]
	global_store_dword v[36:37], v77, off
	global_store_dword v[36:37], v42, off offset:512
	global_store_dword v[36:37], v43, off offset:1024
	global_store_dword v[36:37], v44, off offset:1536
	global_store_dword v[36:37], v45, off offset:2048
	global_store_dword v[36:37], v46, off offset:2560
	global_store_dword v[36:37], v47, off offset:3072
	global_store_dword v[36:37], v48, off offset:3584
	s_waitcnt lgkmcnt(0)
	s_barrier
	ds_read2st64_b32 v[36:37], v30 offset0:64 offset1:80
	ds_read_b32 v38, v28 offset:12288
	ds_read_b32 v39, v30 offset:24576
	s_waitcnt lgkmcnt(1)
	v_add_f32_e32 v36, v38, v36
	s_waitcnt lgkmcnt(0)
	v_add_f32_e32 v37, v37, v39
	v_add_f32_e32 v36, v36, v37
	v_mul_f32_e32 v37, v36, v36
	ds_bpermute_b32 v37, v24, v37
	s_waitcnt lgkmcnt(0)
	v_fmac_f32_e32 v37, v36, v36
	ds_bpermute_b32 v38, v25, v37
	s_waitcnt lgkmcnt(0)
	v_add_f32_e32 v37, v37, v38
	ds_bpermute_b32 v38, v26, v37
	s_waitcnt lgkmcnt(0)
	v_add_f32_e32 v37, v37, v38
	ds_bpermute_b32 v38, v27, v37
	s_waitcnt lgkmcnt(0)
	v_add_f32_e32 v37, v37, v38
	ds_bpermute_b32 v38, v22, v37
	s_waitcnt lgkmcnt(0)
	v_add_f32_e32 v37, v37, v38
	ds_bpermute_b32 v38, v23, v37
	s_and_saveexec_b64 s[0:1], vcc
	s_cbranch_execz .LBB0_636
	s_waitcnt lgkmcnt(0)
	v_add_f32_e32 v37, v37, v38
	v_mov_b32_e32 v38, s2
	ds_write_b32 v38, v37 offset:28672

; #define GAS __attribute__((address_space(1)))
; __device__ __forceinline__ unsigned pk2(float lo, float hi) { const pkf2_t v = {lo, hi}; const pkb2_t b = __builtin_convertvector(v, pkb2_t); return __builtin_bit_cast(unsigned, b); }
; __device__ __forceinline__ f32x4 mma16(bf16x8 a, bf16x8 b, f32x4 c) { return __builtin_amdgcn_mfma_f32_16x16x32_bf16(a, b, c, 0, 0, 0); }
; __device__ __forceinline__ void xattn_sample(Frame& F) {
;     ...
;     for (int u = blockIdx.x; u < 512; u += F.G) {
;         const int b = u >> 2, h = u & 3, row0 = TP + 8 * b;
;         bf16x8 qf[2];
; #pragma unroll
;         for (int ks = 0; ks < 2; ++ks) qf[ks] = *(const GAS bf16x8*)(F.QX + (size_t)(row0 + (l15 & 7)) * 256 + h * 64 + 32 * ks + 8 * lq);
;         f32x4 s[2];
; #pragma unroll
;         for (int t2 = 0; t2 < 2; ++t2) { s[t2] = (f32x4){0.f, 0.f, 0.f, 0.f};
; #pragma unroll
;             for (int ks = 0; ks < 2; ++ks) { const float* kp = F.cache_k + (((size_t)b * 256 + 32 * w + 16 * t2 + l15) * 4 + h) * 64 + 32 * ks + 8 * lq;
;                 const f32x4 x0 = *(const GAS f32x4*)kp, x1 = *(const GAS f32x4*)(kp + 4);
;                 s[t2] = mma16(frag_from(pk2(x0[0], x0[1]), pk2(x0[2], x0[3]), pk2(x1[0], x1[1]), pk2(x1[2], x1[3])), qf[ks], s[t2]); } }
;         float vv[4][8];
; #pragma unroll
;         for (int dt = 0; dt < 4; ++dt)
; #pragma unroll
;             for (int j = 0; j < 8; ++j) vv[dt][j] = F.cache_v[(((size_t)b * 256 + 32 * w + 16 * (j >> 2) + 4 * lq + (j & 3)) * 4 + h) * 64 + 16 * dt + l15];
;         float m = fmaxf(fmaxf(fmaxf(s[0][0], s[0][1]), fmaxf(s[0][2], s[0][3])), fmaxf(fmaxf(s[1][0], s[1][1]), fmaxf(s[1][2], s[1][3])));
;         m = fmaxf(m, __shfl_xor(m, 16)); m = fmaxf(m, __shfl_xor(m, 32));
.LBB0_640:
	s_ashr_i32 s2, s13, 2
	s_lshl_b32 s14, s2, 3
	s_addk_i32 s14, 0x4000
	v_or_b32_e32 v2, s14, v24
	v_ashrrev_i32_e32 v3, 31, v2
	v_readlane_b32 s16, v255, 3
	v_lshlrev_b64 v[2:3], 9, v[2:3]
	v_readlane_b32 s17, v255, 4
	s_and_b32 s15, s10, 0xc0
	s_lshl_b32 s4, s15, 1
	v_lshl_add_u64 v[2:3], s[16:17], 0, v[2:3]
	v_lshl_add_u64 v[2:3], v[2:3], 0, s[4:5]
	s_ashr_i32 s3, s2, 31
	v_lshl_add_u64 v[6:7], v[2:3], 0, v[20:21]
	s_lshl_b64 s[2:3], s[2:3], 8
	global_load_dwordx4 v[2:5], v[6:7], off nt
	global_load_dwordx4 v[64:67], v[6:7], off offset:64 nt
	v_lshl_add_u64 v[6:7], s[2:3], 0, v[12:13]
	s_lshl_b32 s16, s15, 2
	s_mov_b32 s17, s5
	v_lshl_add_u64 v[8:9], v[16:17], 0, s[16:17]
	v_lshlrev_b64 v[6:7], 10, v[6:7]
	v_lshl_add_u64 v[32:33], v[8:9], 0, v[6:7]
	v_add_co_u32_e32 v36, vcc, s12, v32
	global_load_dwordx4 v[6:9], v[32:33], off offset:16 nt
	global_load_dwordx4 v[68:71], v[32:33], off nt
	global_load_dwordx4 v[72:75], v[32:33], off offset:144 nt
	global_load_dwordx4 v[76:79], v[32:33], off offset:128 nt
	v_lshl_add_u64 v[34:35], v[32:33], 0, s[6:7]
	v_addc_co_u32_e32 v37, vcc, 0, v33, vcc
	v_lshl_add_u64 v[32:33], v[32:33], 0, s[8:9]
	global_load_dwordx4 v[80:83], v[36:37], off nt
	global_load_dwordx4 v[84:87], v[34:35], off offset:16 nt
	global_load_dwordx4 v[88:91], v[36:37], off offset:128 nt
	global_load_dwordx4 v[92:95], v[32:33], off offset:16 nt
	v_lshl_add_u64 v[32:33], s[2:3], 0, v[14:15]
	v_lshl_add_u64 v[34:35], v[18:19], 0, s[16:17]
	v_lshlrev_b64 v[32:33], 10, v[32:33]
	v_lshl_add_u64 v[46:47], v[34:35], 0, v[32:33]
	v_add_co_u32_e32 v96, vcc, s12, v46
	s_waitcnt vmcnt(6)
	v_cvt_pk_bf16_f32 v68, v68, v69
	v_addc_co_u32_e32 v97, vcc, 0, v47, vcc
	global_load_dword v39, v[46:47], off nt
	global_load_dword v40, v[46:47], off offset:1024 nt
	global_load_dword v37, v[46:47], off offset:64 nt
	global_load_dword v38, v[46:47], off offset:1088 nt
	global_load_dword v33, v[46:47], off offset:128 nt
	global_load_dword v34, v[46:47], off offset:1152 nt
	global_load_dword v31, v[46:47], off offset:1216 nt
	global_load_dword v32, v[46:47], off offset:192 nt
	global_load_dword v55, v[46:47], off offset:2048 nt
	global_load_dword v56, v[46:47], off offset:3072 nt
	global_load_dword v49, v[46:47], off offset:2112 nt
	global_load_dword v50, v[46:47], off offset:3136 nt
	global_load_dword v42, v[46:47], off offset:2176 nt
	global_load_dword v44, v[46:47], off offset:3200 nt
	global_load_dword v35, v[46:47], off offset:3264 nt
	global_load_dword v36, v[46:47], off offset:2240 nt
	global_load_dword v59, v[96:97], off nt
	global_load_dword v60, v[96:97], off offset:1024 nt
	global_load_dword v53, v[96:97], off offset:64 nt
	global_load_dword v54, v[96:97], off offset:1088 nt
	s_nop 0
	global_load_dword v46, v[96:97], off offset:128 nt
	global_load_dword v48, v[96:97], off offset:1152 nt
	global_load_dword v41, v[96:97], off offset:1216 nt
	global_load_dword v43, v[96:97], off offset:192 nt
	global_load_dword v61, v[96:97], off offset:2048 nt
	global_load_dword v62, v[96:97], off offset:3072 nt
	global_load_dword v57, v[96:97], off offset:2112 nt
	global_load_dword v58, v[96:97], off offset:3136 nt
	global_load_dword v51, v[96:97], off offset:2176 nt
	global_load_dword v52, v[96:97], off offset:3200 nt
	global_load_dword v45, v[96:97], off offset:3264 nt
	global_load_dword v47, v[96:97], off offset:2240 nt
	v_cvt_pk_bf16_f32 v69, v70, v71
	v_cvt_pk_bf16_f32 v70, v6, v7
	v_cvt_pk_bf16_f32 v71, v8, v9
	s_waitcnt vmcnt(35)
	v_cvt_pk_bf16_f32 v80, v80, v81
	v_cvt_pk_bf16_f32 v81, v82, v83
	s_waitcnt vmcnt(34)
	v_cvt_pk_bf16_f32 v82, v84, v85
	v_cvt_pk_bf16_f32 v83, v86, v87
	v_cvt_pk_bf16_f32 v6, v76, v77
	v_cvt_pk_bf16_f32 v7, v78, v79
	v_cvt_pk_bf16_f32 v8, v72, v73
	v_cvt_pk_bf16_f32 v9, v74, v75
	v_mfma_f32_16x16x32_bf16 v[68:71], v[68:71], v[2:5], 0
	s_waitcnt vmcnt(33)
	v_cvt_pk_bf16_f32 v72, v88, v89
	v_cvt_pk_bf16_f32 v73, v90, v91
	s_waitcnt vmcnt(32)
	v_cvt_pk_bf16_f32 v74, v92, v93
	v_cvt_pk_bf16_f32 v75, v94, v95
	v_mfma_f32_16x16x32_bf16 v[2:5], v[80:83], v[2:5], 0
	v_mfma_f32_16x16x32_bf16 v[6:9], v[6:9], v[64:67], v[68:71]
	v_mfma_f32_16x16x32_bf16 v[2:5], v[72:75], v[64:67], v[2:5]
	s_nop 6
	v_max_f32_e32 v63, v7, v7
	v_max_f32_e32 v64, v6, v6
	v_max_f32_e32 v65, v9, v9
	v_max_f32_e32 v66, v8, v8
	v_max_f32_e32 v63, v64, v63
	v_max_f32_e32 v64, v66, v65
	v_max_f32_e32 v65, v5, v5
	v_max_f32_e32 v66, v4, v4
	v_max_f32_e32 v65, v66, v65
	v_max3_f32 v65, v2, v3, v65
	v_max3_f32 v63, v63, v64, v65
	ds_bpermute_b32 v64, v22, v63
	s_waitcnt lgkmcnt(0)
	v_max_f32_e32 v64, v64, v64
	v_max_f32_e32 v63, v63, v64
	ds_bpermute_b32 v64, v23, v63
	s_and_saveexec_b64 s[2:3], s[0:1]
	s_cbranch_execz .LBB0_642
	s_waitcnt lgkmcnt(0)
	v_max_f32_e32 v64, v64, v64
	v_max_f32_e32 v63, v63, v63
	v_max_f32_e32 v63, v63, v64
	ds_write_b32 v30, v63
